# no vmcnt(0) (store acks) before the workgroup barrier that opens the P2 gate GEMM
# baseline (speedup 1.0000x reference)
; __global__ void __launch_bounds__(NTHREADS, 2) hybrid_fwd(Args args) {
;     ...
;             asm volatile("s_waitcnt vmcnt(0) lgkmcnt(0)" ::: "memory"); __syncthreads();
;             pg8::gemm_phase<pg8::EpiProj, pg8::ListOrder, true, true>(lds, gg, S, EG);
.LBB0_667:
	s_waitcnt lgkmcnt(0)
	s_nop 0
	v_mov_b32_e32 v8, v188
	s_cmpk_lt_u32 s46, 0x200
	s_waitcnt lgkmcnt(0)
	s_barrier
	s_cselect_b64 s[0:1], -1, 0
	s_cmpk_gt_u32 s46, 0x1ff
	v_readfirstlane_b32 s6, v8
	s_cbranch_scc1 .LBB0_669
	s_lshl_b32 s2, s46, 3
	s_and_b32 s2, s2, 56
	s_bfe_u32 s3, s46, 0x30003
	s_or_b32 s2, s2, s3
	s_lshr_b32 s4, s46, 6
